# scan loop: LDS-DMA issue moved off the LDS-read to MFMA path (issued just before each barrier wait)
# speedup vs baseline: 1.0044x; 1.0044x over previous
.Lscan_loop:
	s_and_b32 s7, s6, 3
	s_lshl_b32 s7, s7, 12
	v_add_u32_e32 v23, s7, v22
	ds_read_b128 v[32:35], v10 offset:0
	ds_read_b128 v[48:51], v11 offset:0
	ds_read_b128 v[36:39], v10 offset:64
	ds_read_b128 v[52:55], v12 offset:0
	ds_read_b128 v[40:43], v10 offset:128
	ds_read_b128 v[56:59], v13 offset:0
	ds_read_b128 v[44:47], v10 offset:192
	ds_read_b128 v[60:63], v14 offset:0
	ds_read_u16 v80, v23 offset:0
	ds_read_u16 v81, v23 offset:64
	ds_read_u16 v82, v23 offset:128
	ds_read_u16 v83, v23 offset:192
	s_add_u32 s33, s6, 1
	s_min_u32 s33, s33, 31
	s_add_u32 s36, s6, 2
	s_min_u32 s36, s36, 31
	v_readlane_b32 s37, v24, s6
	s_nop 1
	v_mul_f32_e32 v92, s37, v92
	v_mul_f32_e32 v93, s37, v93
	v_mul_f32_e32 v94, s37, v94
	v_mul_f32_e32 v95, s37, v95
	v_mul_f32_e32 v96, s37, v96
	v_mul_f32_e32 v97, s37, v97
	v_mul_f32_e32 v98, s37, v98
	v_mul_f32_e32 v99, s37, v99
	s_waitcnt lgkmcnt(10)
	v_mfma_f32_16x16x32_bf16 v[84:87], v[48:51], v[32:35], 0
	s_waitcnt lgkmcnt(8)
	v_mfma_f32_16x16x32_bf16 v[84:87], v[52:55], v[36:39], v[84:87]
	s_waitcnt lgkmcnt(6)
	v_mfma_f32_16x16x32_bf16 v[84:87], v[56:59], v[40:43], v[84:87]
	s_waitcnt lgkmcnt(4)
	v_mfma_f32_16x16x32_bf16 v[84:87], v[60:63], v[44:47], v[84:87]
	ds_read_b128 v[64:67], v11 offset:32768
	ds_read_b128 v[68:71], v12 offset:32768
	ds_read_b128 v[72:75], v13 offset:32768
	ds_read_b128 v[76:79], v14 offset:32768
	s_waitcnt lgkmcnt(4)
	v_lshlrev_b32_e32 v80, 16, v80
	v_lshlrev_b32_e32 v81, 16, v81
	v_lshlrev_b32_e32 v82, 16, v82
	v_lshlrev_b32_e32 v83, 16, v83
	v_sub_f32_e32 v26, v80, v84
	v_sub_f32_e32 v27, v81, v85
	v_sub_f32_e32 v28, v82, v86
	v_sub_f32_e32 v29, v83, v87
	v_cvt_pk_bf16_f32 v26, v26, v27
	v_cvt_pk_bf16_f32 v27, v28, v29
	ds_write_b64 v20, v[26:27]
	s_lshl_b32 s7, s33, 14
	s_add_u32 s26, s14, s7
	s_addc_u32 s27, s15, 0
	s_add_i32 m0, s30, 0x14000
	s_nop 0
	global_load_lds_dwordx4 v5, s[26:27]
	s_add_i32 m0, s30, 0x14400
	s_nop 0
	global_load_lds_dwordx4 v6, s[26:27]
	s_lshl_b32 s7, s33, 13
	s_add_u32 s28, s18, s7
	s_addc_u32 s29, s19, 0
	s_add_i32 m0, s31, 0x1a000
	s_nop 0
	global_load_lds_dwordx4 v7, s[28:29]
	s_lshl_b32 s7, s36, 14
	s_add_u32 s26, s24, s7
	s_addc_u32 s27, s25, 0
	s_add_u32 s8, s6, 2
	s_and_b32 s8, s8, 3
	s_lshl_b32 s8, s8, 12
	s_add_u32 s8, s8, s32
	s_add_i32 m0, s8, 0x1f400
	s_nop 0
	global_load_lds_dwordx4 v8, s[26:27]
	s_waitcnt vmcnt(10) lgkmcnt(0)
	s_barrier
	ds_read_b128 v[100:103], v19
	ds_read_b128 v[108:111], v15 offset:0
	ds_read_b128 v[112:115], v15 offset:2048
	ds_read_b128 v[104:107], v19 offset:64
	ds_read_b128 v[116:119], v16 offset:0
	ds_read_b128 v[120:123], v16 offset:2048
	ds_read_b128 v[124:127], v17 offset:0
	ds_read_b128 v[128:131], v18 offset:0
	v_mfma_f32_16x16x32_bf16 v[88:91], v[32:35], v[64:67], 0
	v_mfma_f32_16x16x32_bf16 v[88:91], v[36:39], v[68:71], v[88:91]
	v_mfma_f32_16x16x32_bf16 v[88:91], v[40:43], v[72:75], v[88:91]
	v_mfma_f32_16x16x32_bf16 v[88:91], v[44:47], v[76:79], v[88:91]
	s_waitcnt lgkmcnt(6)
	v_mfma_f32_16x16x32_bf16 v[92:95], v[108:111], v[100:103], v[92:95]
	s_waitcnt lgkmcnt(5)
	v_mfma_f32_16x16x32_bf16 v[96:99], v[112:115], v[100:103], v[96:99]
	s_waitcnt lgkmcnt(3)
	v_mfma_f32_16x16x32_bf16 v[92:95], v[116:119], v[104:107], v[92:95]
	s_waitcnt lgkmcnt(2)
	v_mfma_f32_16x16x32_bf16 v[96:99], v[120:123], v[104:107], v[96:99]
	s_waitcnt lgkmcnt(1)
	v_mfma_f32_16x16x32_bf16 v[88:91], v[100:103], v[124:127], v[88:91]
	s_waitcnt lgkmcnt(0)
	v_mfma_f32_16x16x32_bf16 v[88:91], v[104:107], v[128:131], v[88:91]
	s_lshl_b32 s7, s6, 14
	s_add_u32 s28, s24, s7
	s_addc_u32 s29, s25, 0
	s_nop 1
	v_cvt_pk_bf16_f32 v26, v92, v93
	v_cvt_pk_bf16_f32 v27, v94, v95
	v_cvt_pk_bf16_f32 v28, v96, v97
	v_cvt_pk_bf16_f32 v29, v98, v99
	ds_write_b64 v21, v[26:27]
	ds_write_b64 v21, v[28:29] offset:32
	s_lshl_b32 s7, s36, 14
	s_add_u32 s26, s10, s7
	s_addc_u32 s27, s11, 0
	s_add_i32 m0, s30, 0x0
	s_nop 0
	global_load_lds_dwordx4 v3, s[26:27]
	s_add_i32 m0, s30, 0x400
	s_nop 0
	global_load_lds_dwordx4 v4, s[26:27]
	s_lshl_b32 s7, s36, 14
	s_add_u32 s26, s12, s7
	s_addc_u32 s27, s13, 0
	s_add_i32 m0, s30, 0x8000
	s_nop 0
	global_load_lds_dwordx4 v3, s[26:27]
	s_add_i32 m0, s30, 0x8400
	s_nop 0
	global_load_lds_dwordx4 v4, s[26:27]
	v_cvt_pk_bf16_f32 v80, v88, v89
	v_cvt_pk_bf16_f32 v81, v90, v91
	global_store_dwordx2 v9, v[80:81], s[28:29]
	s_add_u32 s6, s6, 1
	s_waitcnt vmcnt(10) lgkmcnt(0)
	s_barrier
	s_and_b32 s7, s6, 3
	s_lshl_b32 s7, s7, 12
	v_add_u32_e32 v23, s7, v22
	ds_read_b128 v[32:35], v10 offset:0
	ds_read_b128 v[48:51], v11 offset:16384
	ds_read_b128 v[36:39], v10 offset:64
	ds_read_b128 v[52:55], v12 offset:16384
	ds_read_b128 v[40:43], v10 offset:128
	ds_read_b128 v[56:59], v13 offset:16384
	ds_read_b128 v[44:47], v10 offset:192
	ds_read_b128 v[60:63], v14 offset:16384
	ds_read_u16 v80, v23 offset:0
	ds_read_u16 v81, v23 offset:64
	ds_read_u16 v82, v23 offset:128
	ds_read_u16 v83, v23 offset:192
	s_add_u32 s33, s6, 1
	s_min_u32 s33, s33, 31
	s_add_u32 s36, s6, 2
	s_min_u32 s36, s36, 31
	v_readlane_b32 s37, v24, s6
	s_nop 1
	v_mul_f32_e32 v92, s37, v92
	v_mul_f32_e32 v93, s37, v93
	v_mul_f32_e32 v94, s37, v94
	v_mul_f32_e32 v95, s37, v95
	v_mul_f32_e32 v96, s37, v96
	v_mul_f32_e32 v97, s37, v97
	v_mul_f32_e32 v98, s37, v98
	v_mul_f32_e32 v99, s37, v99
	s_waitcnt lgkmcnt(10)
	v_mfma_f32_16x16x32_bf16 v[84:87], v[48:51], v[32:35], 0
	s_waitcnt lgkmcnt(8)
	v_mfma_f32_16x16x32_bf16 v[84:87], v[52:55], v[36:39], v[84:87]
	s_waitcnt lgkmcnt(6)
	v_mfma_f32_16x16x32_bf16 v[84:87], v[56:59], v[40:43], v[84:87]
	s_waitcnt lgkmcnt(4)
	v_mfma_f32_16x16x32_bf16 v[84:87], v[60:63], v[44:47], v[84:87]
	ds_read_b128 v[64:67], v11 offset:49152
	ds_read_b128 v[68:71], v12 offset:49152
	ds_read_b128 v[72:75], v13 offset:49152
	ds_read_b128 v[76:79], v14 offset:49152
	s_waitcnt lgkmcnt(4)
	v_lshlrev_b32_e32 v80, 16, v80
	v_lshlrev_b32_e32 v81, 16, v81
	v_lshlrev_b32_e32 v82, 16, v82
	v_lshlrev_b32_e32 v83, 16, v83
	v_sub_f32_e32 v26, v80, v84
	v_sub_f32_e32 v27, v81, v85
	v_sub_f32_e32 v28, v82, v86
	v_sub_f32_e32 v29, v83, v87
	v_cvt_pk_bf16_f32 v26, v26, v27
	v_cvt_pk_bf16_f32 v27, v28, v29
	ds_write_b64 v20, v[26:27]
	s_lshl_b32 s7, s33, 14
	s_add_u32 s26, s14, s7
	s_addc_u32 s27, s15, 0
	s_add_i32 m0, s30, 0x10000
	s_nop 0
	global_load_lds_dwordx4 v5, s[26:27]
	s_add_i32 m0, s30, 0x10400
	s_nop 0
	global_load_lds_dwordx4 v6, s[26:27]
	s_lshl_b32 s7, s33, 13
	s_add_u32 s28, s18, s7
	s_addc_u32 s29, s19, 0
	s_add_i32 m0, s31, 0x18000
	s_nop 0
	global_load_lds_dwordx4 v7, s[28:29]
	s_lshl_b32 s7, s36, 14
	s_add_u32 s26, s24, s7
	s_addc_u32 s27, s25, 0
	s_add_u32 s8, s6, 2
	s_and_b32 s8, s8, 3
	s_lshl_b32 s8, s8, 12
	s_add_u32 s8, s8, s32
	s_add_i32 m0, s8, 0x1f400
	s_nop 0
	global_load_lds_dwordx4 v8, s[26:27]
	s_waitcnt vmcnt(10) lgkmcnt(0)
	s_barrier
	ds_read_b128 v[100:103], v19
	ds_read_b128 v[108:111], v15 offset:16384
	ds_read_b128 v[112:115], v15 offset:18432
	ds_read_b128 v[104:107], v19 offset:64
	ds_read_b128 v[116:119], v16 offset:16384
	ds_read_b128 v[120:123], v16 offset:18432
	ds_read_b128 v[124:127], v17 offset:8192
	ds_read_b128 v[128:131], v18 offset:8192
	v_mfma_f32_16x16x32_bf16 v[88:91], v[32:35], v[64:67], 0
	v_mfma_f32_16x16x32_bf16 v[88:91], v[36:39], v[68:71], v[88:91]
	v_mfma_f32_16x16x32_bf16 v[88:91], v[40:43], v[72:75], v[88:91]
	v_mfma_f32_16x16x32_bf16 v[88:91], v[44:47], v[76:79], v[88:91]
	s_waitcnt lgkmcnt(6)
	v_mfma_f32_16x16x32_bf16 v[92:95], v[108:111], v[100:103], v[92:95]
	s_waitcnt lgkmcnt(5)
	v_mfma_f32_16x16x32_bf16 v[96:99], v[112:115], v[100:103], v[96:99]
	s_waitcnt lgkmcnt(3)
	v_mfma_f32_16x16x32_bf16 v[92:95], v[116:119], v[104:107], v[92:95]
	s_waitcnt lgkmcnt(2)
	v_mfma_f32_16x16x32_bf16 v[96:99], v[120:123], v[104:107], v[96:99]
	s_waitcnt lgkmcnt(1)
	v_mfma_f32_16x16x32_bf16 v[88:91], v[100:103], v[124:127], v[88:91]
	s_waitcnt lgkmcnt(0)
	v_mfma_f32_16x16x32_bf16 v[88:91], v[104:107], v[128:131], v[88:91]
	s_lshl_b32 s7, s6, 14
	s_add_u32 s28, s24, s7
	s_addc_u32 s29, s25, 0
	s_nop 1
	v_cvt_pk_bf16_f32 v26, v92, v93
	v_cvt_pk_bf16_f32 v27, v94, v95
	v_cvt_pk_bf16_f32 v28, v96, v97
	v_cvt_pk_bf16_f32 v29, v98, v99
	ds_write_b64 v21, v[26:27]
	ds_write_b64 v21, v[28:29] offset:32
	s_lshl_b32 s7, s36, 14
	s_add_u32 s26, s10, s7
	s_addc_u32 s27, s11, 0
	s_add_i32 m0, s30, 0x4000
	s_nop 0
	global_load_lds_dwordx4 v3, s[26:27]
	s_add_i32 m0, s30, 0x4400
	s_nop 0
	global_load_lds_dwordx4 v4, s[26:27]
	s_lshl_b32 s7, s36, 14
	s_add_u32 s26, s12, s7
	s_addc_u32 s27, s13, 0
	s_add_i32 m0, s30, 0xc000
	s_nop 0
	global_load_lds_dwordx4 v3, s[26:27]
	s_add_i32 m0, s30, 0xc400
	s_nop 0
	global_load_lds_dwordx4 v4, s[26:27]
	v_cvt_pk_bf16_f32 v80, v88, v89
	v_cvt_pk_bf16_f32 v81, v90, v91
	global_store_dwordx2 v9, v[80:81], s[28:29]
	s_add_u32 s6, s6, 1
	s_waitcnt vmcnt(10) lgkmcnt(0)
	s_barrier
	s_cmp_lt_u32 s6, 32
	s_cbranch_scc1 .Lscan_loop
	s_lshl_b32 s56, s77, 5
	s_and_b32 s57, s40, 3
	s_lshl_b32 s72, s40, 5
	s_waitcnt vmcnt(0)
	v_readfirstlane_b32 s3, v194
	s_cmp_gt_u32 s3, 63
	s_barrier
	s_cbranch_scc1 .LBB0_421
	s_waitcnt vmcnt(2)
	v_mbcnt_lo_u32_b32 v0, -1, 0
	v_mbcnt_hi_u32_b32 v0, -1, v0
	s_nop 0
	v_cmp_eq_u32_e32 vcc, 0, v0
	s_and_saveexec_b64 s[6:7], vcc
	s_cbranch_execz .LBB0_420
	s_add_i32 s3, 0, 0x23ff0
	v_mov_b32_e32 v0, s3
	s_waitcnt vmcnt(0) expcnt(0) lgkmcnt(0)
	ds_read_b32 v2, v0
	s_add_i32 s3, 0, 0x23ff4
	v_mov_b32_e32 v0, s3
	ds_read_b32 v0, v0
	s_waitcnt lgkmcnt(1)
	v_cmp_ne_u32_e32 vcc, 0, v2
	s_cbranch_vccnz .LBB0_384
	s_mov_b32 s3, 1
	v_mov_b32_e32 v16, 0
	s_branch .LBB0_372
